# scan: software L2 prefetch (touch chunk n+2 each step), egl one step ahead, pinned scans, prio
# baseline (speedup 1.0000x reference)
.LBB0_487:
	s_and_b64 vcc, exec, s[0:1]
	s_cbranch_vccz .LBB0_397
	s_setprio 3
	v_mov_b32_e32 v76, v198
	v_mov_b64_e32 v[4:5], s[16:17]
	flat_load_dwordx2 v[100:101], v[4:5]
	s_lshl_b32 s4, s75, 6
	s_and_b32 s0, s75, 1
	s_ashr_i32 s1, s75, 3
	s_and_b32 s4, s4, 0xffffff80
	v_add_u32_e32 v78, 0x100, v76
	v_add_u32_e32 v84, 0x200, v76
	v_add_u32_e32 v86, 0x300, v76
	v_add_u32_e32 v88, 0x400, v76
	v_add_u32_e32 v90, 0x500, v76
	v_add_u32_e32 v92, 0x600, v76
	v_add_u32_e32 v94, 0x700, v76
	s_mul_hi_i32 s7, s1, 0x3800000
	s_mul_i32 s8, s1, 0x3800000
	s_lshl_b32 s9, s0, 6
	s_lshl_b32 s18, s0, 13
	v_ashrrev_i32_e32 v77, 31, v76
	v_ashrrev_i32_e32 v79, 31, v78
	v_ashrrev_i32_e32 v85, 31, v84
	v_ashrrev_i32_e32 v87, 31, v86
	v_ashrrev_i32_e32 v89, 31, v88
	v_ashrrev_i32_e32 v91, 31, v90
	v_ashrrev_i32_e32 v93, 31, v92
	v_ashrrev_i32_e32 v95, 31, v94
	v_lshlrev_b64 v[96:97], 4, v[76:77]
	v_lshlrev_b64 v[98:99], 4, v[78:79]
	v_lshlrev_b64 v[110:111], 4, v[84:85]
	v_lshlrev_b64 v[108:109], 4, v[86:87]
	v_lshlrev_b64 v[106:107], 4, v[88:89]
	v_lshlrev_b64 v[104:105], 4, v[90:91]
	v_lshlrev_b64 v[122:123], 4, v[92:93]
	v_lshlrev_b64 v[120:121], 4, v[94:95]
	s_lshl_b32 s5, s75, 7
	s_and_b32 s10, s5, 0x300
	s_ashr_i32 s5, s4, 31
	v_and_b32_e32 v79, 63, v76
	v_bfe_u32 v87, v76, 4, 2
	v_ashrrev_i32_e32 v77, 6, v76
	s_mul_i32 s52, s4, 0x12000
	v_lshlrev_b32_e32 v78, 4, v78
	v_lshlrev_b32_e32 v89, 4, v90
	v_lshlrev_b32_e32 v90, 4, v92
	v_lshl_add_u32 v2, v79, 4, 0
	v_lshlrev_b32_e32 v92, 3, v79
	v_mul_hi_u32_u24_e32 v79, 0x7000, v87
	v_mul_u32_u24_e32 v87, 0x7000, v87
	v_and_b32_e32 v85, 15, v76
	s_mul_hi_i32 s11, s4, 0x12000
	v_lshlrev_b32_e32 v1, 4, v76
	v_lshl_add_u32 v76, v77, 4, s9
	v_add_u32_e32 v124, 0, v78
	v_or_b32_e32 v79, s7, v79
	v_or_b32_e32 v78, s8, v87
	v_mad_i64_i32 v[102:103], s[8:9], s4, v210, v[96:97]
	v_lshl_add_u32 v93, v77, 11, 0
	v_ashrrev_i32_e32 v77, 31, v76
	v_or_b32_e32 v78, s10, v78
	v_mov_b32_e32 v4, 0
	v_lshlrev_b32_e32 v84, 4, v84
	v_lshlrev_b32_e32 v86, 4, v86
	v_lshlrev_b32_e32 v88, 4, v88
	v_lshlrev_b32_e32 v91, 4, v94
	v_lshl_add_u64 v[114:115], v[76:77], 1, v[78:79]
	s_movk_i32 s6, 0x7f
	v_mov_b32_e32 v5, v4
	v_mov_b32_e32 v6, v4
	v_mov_b32_e32 v7, v4
	v_mov_b32_e32 v16, v4
	v_mov_b32_e32 v17, v4
	v_mov_b32_e32 v18, v4
	v_mov_b32_e32 v19, v4
	v_add_u32_e32 v1, 0, v1
	v_add_u32_e32 v125, 0, v84
	v_add_u32_e32 v126, 0, v86
	v_add_u32_e32 v127, 0, v88
	v_add_u32_e32 v128, 0, v89
	v_add_u32_e32 v129, 0, v90
	v_add_u32_e32 v130, 0, v91
	v_add_u32_e32 v131, v93, v92
	s_waitcnt vmcnt(0) lgkmcnt(0)
	v_readfirstlane_b32 s86, v100
	v_readfirstlane_b32 s87, v101
	v_mad_i64_i32 v[8:9], s[0:1], s4, v210, v[100:101]
	v_lshl_add_u64 v[10:11], v[8:9], 0, s[34:35]
	v_and_b32_e32 v238, 63, v198
	v_lshlrev_b32_e32 v238, 8, v238
	v_lshrrev_b32_e32 v239, 6, v198
	v_lshl_add_u32 v238, v239, 14, v238
	v_mov_b32_e32 v239, s18
	v_cmp_lt_u32_e32 vcc, 223, v198
	s_nop 1
	v_cndmask_b32_e32 v239, 0, v239, vcc
	v_add_u32_e32 v238, v238, v239
	v_mov_b32_e32 v239, 0
	v_lshl_add_u64 v[236:237], v[238:239], 0, v[10:11]
	v_lshl_add_u64 v[236:237], v[236:237], 0, s[50:51]
	v_lshl_add_u64 v[236:237], v[236:237], 0, s[50:51]
	v_lshl_add_u64 v[8:9], v[8:9], 0, s[44:45]
	v_lshl_add_u64 v[12:13], v[10:11], 0, v[96:97]
	v_lshl_add_u64 v[14:15], v[10:11], 0, v[98:99]
	v_lshl_add_u64 v[20:21], v[10:11], 0, v[110:111]
	v_lshl_add_u64 v[24:25], v[10:11], 0, v[108:109]
	v_lshl_add_u64 v[28:29], v[10:11], 0, v[106:107]
	v_lshl_add_u64 v[32:33], v[10:11], 0, v[104:105]
	v_lshl_add_u64 v[36:37], v[10:11], 0, v[122:123]
	v_lshl_add_u64 v[40:41], v[10:11], 0, v[120:121]
	v_lshl_add_u64 v[30:31], v[8:9], 0, v[96:97]
	v_lshl_add_u64 v[34:35], v[8:9], 0, v[98:99]
	v_lshl_add_u64 v[38:39], v[8:9], 0, v[110:111]
	v_lshl_add_u64 v[42:43], v[8:9], 0, v[108:109]
	v_lshl_add_u64 v[44:45], v[8:9], 0, v[106:107]
	v_lshl_add_u64 v[72:73], v[10:11], 0, s[18:19]
	v_lshl_add_u64 v[46:47], v[8:9], 0, v[104:105]
	global_load_dwordx4 v[8:11], v[12:13], off
	s_nop 0
	global_load_dwordx4 v[12:15], v[14:15], off
	s_nop 0
	global_load_dwordx4 v[20:23], v[20:21], off
	s_nop 0
	global_load_dwordx4 v[24:27], v[24:25], off
	s_nop 0
	global_load_dwordx4 v[48:51], v[30:31], off
	global_load_dwordx4 v[52:55], v[34:35], off
	s_nop 0
	global_load_dwordx4 v[28:31], v[28:29], off
	s_nop 0
	global_load_dwordx4 v[32:35], v[32:33], off
	s_nop 0
	global_load_dwordx4 v[56:59], v[38:39], off
	global_load_dwordx4 v[60:63], v[42:43], off
	s_nop 0
	global_load_dwordx4 v[36:39], v[36:37], off
	s_nop 0
	global_load_dwordx4 v[40:43], v[40:41], off
	s_nop 0
	global_load_dwordx4 v[64:67], v[44:45], off
	global_load_dwordx4 v[68:71], v[46:47], off
	v_lshl_add_u64 v[44:45], v[72:73], 0, s[46:47]
	v_lshl_add_u64 v[46:47], v[44:45], 0, v[96:97]
	v_lshl_add_u64 v[44:45], v[44:45], 0, v[98:99]
	global_load_dwordx4 v[72:75], v[46:47], off
	global_load_dwordx4 v[80:83], v[44:45], off
	s_lshl_b64 s[0:1], s[4:5], 2
	s_add_u32 s0, s0, 0x2ce00000
	s_addc_u32 s1, s1, 0
	s_or_b32 s7, s52, s18
	v_mad_i64_i32 v[104:105], s[8:9], s4, v210, v[104:105]
	v_mad_i64_i32 v[106:107], s[8:9], s4, v210, v[106:107]
	v_mad_i64_i32 v[108:109], s[8:9], s4, v210, v[108:109]
	v_mad_i64_i32 v[110:111], s[8:9], s4, v210, v[110:111]
	v_mad_i64_i32 v[112:113], s[4:5], s4, v210, v[98:99]
	s_add_u32 s4, s7, 0x2e020000
	s_addc_u32 s5, s11, 0
	v_lshl_add_u64 v[116:117], s[4:5], 0, v[98:99]
	v_lshl_add_u64 v[118:119], s[4:5], 0, v[96:97]
	s_add_u32 s4, s52, 0x2e012000
	s_addc_u32 s5, s11, 0
	v_mov_b32_e32 v44, v4
	v_mov_b32_e32 v45, v4
	v_mov_b32_e32 v46, v4
	v_mov_b32_e32 v47, v4
	v_lshl_or_b32 v114, v85, 1, v114
	v_lshl_add_u64 v[120:121], s[4:5], 0, v[120:121]
	v_lshl_add_u64 v[122:123], s[4:5], 0, v[122:123]
	v_mov_b32_e32 v76, v4
	v_mov_b32_e32 v77, v4
	v_mov_b32_e32 v78, v4
	v_mov_b32_e32 v79, v4
	v_mov_b32_e32 v84, v4
	v_mov_b32_e32 v85, v4
	v_mov_b32_e32 v86, v4
	v_mov_b32_e32 v87, v4
	v_mov_b32_e32 v88, v4
	v_mov_b32_e32 v89, v4
	v_mov_b32_e32 v90, v4
	v_mov_b32_e32 v91, v4
	v_mov_b32_e32 v92, v4
	v_mov_b32_e32 v93, v4
	v_mov_b32_e32 v94, v4
	v_mov_b32_e32 v95, v4
	v_mov_b32_e32 v96, v4
	v_mov_b32_e32 v97, v4
	v_mov_b32_e32 v98, v4
	v_mov_b32_e32 v99, v4
	v_lshl_add_u64 v[196:197], v[100:101], 0, s[0:1]
	global_load_dword v196, v[196:197], off
	s_waitcnt vmcnt(15)
	ds_write_b128 v1, v[8:11]
	s_waitcnt vmcnt(11)
	ds_write_b128 v1, v[48:51] offset:32768
	ds_write_b128 v124, v[12:15]
	s_waitcnt vmcnt(10)
	ds_write_b128 v124, v[52:55] offset:32768
	ds_write_b128 v125, v[20:23]
	s_waitcnt vmcnt(7)
	ds_write_b128 v125, v[56:59] offset:32768
	ds_write_b128 v126, v[24:27]
	s_waitcnt vmcnt(6)
	ds_write_b128 v126, v[60:63] offset:32768
	ds_write_b128 v127, v[28:31]
	s_waitcnt vmcnt(3)
	ds_write_b128 v127, v[64:67] offset:32768
	ds_write_b128 v128, v[32:35]
	s_waitcnt vmcnt(2)
	ds_write_b128 v128, v[68:71] offset:32768
	ds_write_b128 v129, v[36:39]
	ds_write_b128 v130, v[40:43]
	s_waitcnt vmcnt(1)
	ds_write_b128 v129, v[72:75] offset:32768
	s_waitcnt vmcnt(0)
	ds_write_b128 v130, v[80:83] offset:32768
	s_waitcnt lgkmcnt(0)
	s_barrier
	s_branch .LBB0_490
.LBB0_489:
	s_add_u32 s0, s0, 4
	s_addc_u32 s1, s1, 0
	s_add_i32 s6, s6, -1
	v_lshl_add_u64 v[236:237], v[236:237], 0, s[50:51]
	v_lshl_add_u64 v[114:115], v[114:115], 0, s[48:49]
	v_lshl_add_u64 v[116:117], v[116:117], 0, s[50:51]
	v_lshl_add_u64 v[118:119], v[118:119], 0, s[50:51]
	v_lshl_add_u64 v[104:105], v[104:105], 0, s[50:51]
	v_lshl_add_u64 v[106:107], v[106:107], 0, s[50:51]
	v_lshl_add_u64 v[108:109], v[108:109], 0, s[50:51]
	v_lshl_add_u64 v[110:111], v[110:111], 0, s[50:51]
	v_lshl_add_u64 v[112:113], v[112:113], 0, s[50:51]
	v_lshl_add_u64 v[102:103], v[102:103], 0, s[50:51]
	v_lshl_add_u64 v[120:121], v[120:121], 0, s[50:51]
	s_cmp_eq_u32 s6, -1
	v_lshl_add_u64 v[122:123], v[122:123], 0, s[50:51]
	s_waitcnt lgkmcnt(0)
	s_barrier
	s_cbranch_scc1 .LBB0_397

.LBB0_492:
	ds_read_b128 v[212:215], v2
	ds_read_b128 v[216:219], v2 offset:4096
	ds_read_b128 v[220:223], v2 offset:8192
	ds_read_b128 v[224:227], v2 offset:12288
	ds_read2st64_b64 v[188:191], v131 offset0:112 offset1:113
	ds_read2st64_b64 v[192:195], v131 offset0:114 offset1:115
	v_cvt_pk_bf16_f32 v132, v16, v17
	v_cvt_pk_bf16_f32 v133, v18, v19
	v_cvt_pk_bf16_f32 v134, v4, v5
	v_cvt_pk_bf16_f32 v135, v6, v7
	v_cvt_pk_bf16_f32 v136, v44, v45
	v_cvt_pk_bf16_f32 v137, v46, v47
	v_cvt_pk_bf16_f32 v138, v76, v77
	v_cvt_pk_bf16_f32 v139, v78, v79
	v_cvt_pk_bf16_f32 v140, v84, v85
	v_cvt_pk_bf16_f32 v141, v86, v87
	v_cvt_pk_bf16_f32 v142, v88, v89
	v_cvt_pk_bf16_f32 v143, v90, v91
	v_cvt_pk_bf16_f32 v144, v92, v93
	v_cvt_pk_bf16_f32 v145, v94, v95
	v_cvt_pk_bf16_f32 v146, v96, v97
	v_cvt_pk_bf16_f32 v147, v98, v99
	v_add_u32_e32 v197, 0x4000c00, v114
	s_waitcnt lgkmcnt(5)
	v_mfma_f32_16x16x32_bf16 v[156:159], v[212:215], v[132:135], 0
	ds_read_b128 v[228:231], v2 offset:1024
	s_waitcnt lgkmcnt(5)
	v_mfma_f32_16x16x32_bf16 v[160:163], v[216:219], v[132:135], 0
	ds_read_b128 v[232:235], v2 offset:5120
	s_waitcnt lgkmcnt(5)
	v_mfma_f32_16x16x32_bf16 v[164:167], v[220:223], v[132:135], 0
	ds_read_b128 v[212:215], v2 offset:9216
	s_waitcnt lgkmcnt(5)
	v_mfma_f32_16x16x32_bf16 v[168:171], v[224:227], v[132:135], 0
	ds_read_b128 v[216:219], v2 offset:13312
	s_waitcnt lgkmcnt(3)
	v_mfma_f32_16x16x32_bf16 v[156:159], v[228:231], v[136:139], v[156:159]
	ds_read_b128 v[220:223], v2 offset:2048
	s_waitcnt lgkmcnt(3)
	v_mfma_f32_16x16x32_bf16 v[160:163], v[232:235], v[136:139], v[160:163]
	ds_read_b128 v[224:227], v2 offset:6144
	s_waitcnt lgkmcnt(3)
	v_mfma_f32_16x16x32_bf16 v[164:167], v[212:215], v[136:139], v[164:167]
	ds_read_b128 v[228:231], v2 offset:10240
	s_waitcnt lgkmcnt(3)
	v_mfma_f32_16x16x32_bf16 v[168:171], v[216:219], v[136:139], v[168:171]
	ds_read_b128 v[232:235], v2 offset:14336
	s_waitcnt lgkmcnt(3)
	v_mfma_f32_16x16x32_bf16 v[156:159], v[220:223], v[140:143], v[156:159]
	ds_read_b128 v[212:215], v2 offset:3072
	s_waitcnt lgkmcnt(3)
	v_mfma_f32_16x16x32_bf16 v[160:163], v[224:227], v[140:143], v[160:163]
	ds_read_b128 v[216:219], v2 offset:7168
	s_waitcnt lgkmcnt(3)
	v_mfma_f32_16x16x32_bf16 v[164:167], v[228:231], v[140:143], v[164:167]
	ds_read_b128 v[220:223], v2 offset:11264
	s_waitcnt lgkmcnt(3)
	v_mfma_f32_16x16x32_bf16 v[168:171], v[232:235], v[140:143], v[168:171]
	ds_read_b128 v[224:227], v2 offset:15360
	s_waitcnt lgkmcnt(3)
	v_mfma_f32_16x16x32_bf16 v[156:159], v[212:215], v[144:147], v[156:159]
	ds_read_b128 v[228:231], v2 offset:16384
	s_waitcnt lgkmcnt(3)
	v_mfma_f32_16x16x32_bf16 v[160:163], v[216:219], v[144:147], v[160:163]
	ds_read_b128 v[232:235], v2 offset:20480
	s_waitcnt lgkmcnt(3)
	v_mfma_f32_16x16x32_bf16 v[164:167], v[220:223], v[144:147], v[164:167]
	ds_read_b128 v[212:215], v2 offset:24576
	s_waitcnt lgkmcnt(3)
	v_mfma_f32_16x16x32_bf16 v[168:171], v[224:227], v[144:147], v[168:171]
	ds_read_b128 v[216:219], v2 offset:28672
	s_waitcnt lgkmcnt(3)
	v_mfma_f32_16x16x32_bf16 v[172:175], v[228:231], v[132:135], 0
	ds_read_b128 v[220:223], v2 offset:17408
	v_pk_mul_f32 v[16:17], v[16:17], v[196:197] op_sel_hi:[1,0]
	v_pk_mul_f32 v[18:19], v[18:19], v[196:197] op_sel_hi:[1,0]
	s_waitcnt lgkmcnt(3)
	v_mfma_f32_16x16x32_bf16 v[176:179], v[232:235], v[132:135], 0
	ds_read_b128 v[224:227], v2 offset:21504
	v_pk_mul_f32 v[4:5], v[4:5], v[196:197] op_sel_hi:[1,0]
	v_pk_mul_f32 v[6:7], v[6:7], v[196:197] op_sel_hi:[1,0]
	s_waitcnt lgkmcnt(3)
	v_mfma_f32_16x16x32_bf16 v[180:183], v[212:215], v[132:135], 0
	ds_read_b128 v[228:231], v2 offset:25600
	v_pk_mul_f32 v[44:45], v[44:45], v[196:197] op_sel_hi:[1,0]
	v_pk_mul_f32 v[46:47], v[46:47], v[196:197] op_sel_hi:[1,0]
	v_lshlrev_b32_e32 v240, 16, v188
	v_and_b32_e32 v241, 0xffff0000, v188
	v_lshlrev_b32_e32 v242, 16, v189
	v_and_b32_e32 v243, 0xffff0000, v189
	s_waitcnt lgkmcnt(3)
	v_mfma_f32_16x16x32_bf16 v[184:187], v[216:219], v[132:135], 0
	ds_read_b128 v[232:235], v2 offset:29696
	v_pk_mul_f32 v[76:77], v[76:77], v[196:197] op_sel_hi:[1,0]
	v_pk_mul_f32 v[78:79], v[78:79], v[196:197] op_sel_hi:[1,0]
	v_sub_f32_e32 v156, v240, v156
	v_sub_f32_e32 v157, v241, v157
	v_sub_f32_e32 v158, v242, v158
	v_sub_f32_e32 v159, v243, v159
	s_waitcnt lgkmcnt(3)
	v_mfma_f32_16x16x32_bf16 v[172:175], v[220:223], v[136:139], v[172:175]
	ds_read_b128 v[212:215], v2 offset:18432
	v_pk_mul_f32 v[84:85], v[84:85], v[196:197] op_sel_hi:[1,0]
	v_pk_mul_f32 v[86:87], v[86:87], v[196:197] op_sel_hi:[1,0]
	v_lshlrev_b32_e32 v240, 16, v190
	v_and_b32_e32 v241, 0xffff0000, v190
	v_lshlrev_b32_e32 v242, 16, v191
	v_and_b32_e32 v243, 0xffff0000, v191
	s_waitcnt lgkmcnt(3)
	v_mfma_f32_16x16x32_bf16 v[176:179], v[224:227], v[136:139], v[176:179]
	ds_read_b128 v[216:219], v2 offset:22528
	v_pk_mul_f32 v[88:89], v[88:89], v[196:197] op_sel_hi:[1,0]
	v_pk_mul_f32 v[90:91], v[90:91], v[196:197] op_sel_hi:[1,0]
	v_sub_f32_e32 v160, v240, v160
	v_sub_f32_e32 v161, v241, v161
	v_sub_f32_e32 v162, v242, v162
	v_sub_f32_e32 v163, v243, v163
	s_waitcnt lgkmcnt(3)
	v_mfma_f32_16x16x32_bf16 v[180:183], v[228:231], v[136:139], v[180:183]
	ds_read_b128 v[220:223], v2 offset:26624
	v_pk_mul_f32 v[92:93], v[92:93], v[196:197] op_sel_hi:[1,0]
	v_pk_mul_f32 v[94:95], v[94:95], v[196:197] op_sel_hi:[1,0]
	v_lshlrev_b32_e32 v240, 16, v192
	v_and_b32_e32 v241, 0xffff0000, v192
	v_lshlrev_b32_e32 v242, 16, v193
	v_and_b32_e32 v243, 0xffff0000, v193
	v_cvt_pk_bf16_f32 v148, v156, v157
	v_cvt_pk_bf16_f32 v149, v158, v159
	v_cvt_pk_bf16_f32 v150, v160, v161
	v_cvt_pk_bf16_f32 v151, v162, v163
	s_waitcnt lgkmcnt(3)
	v_mfma_f32_16x16x32_bf16 v[184:187], v[232:235], v[136:139], v[184:187]
	ds_read_b128 v[224:227], v2 offset:30720
	v_pk_mul_f32 v[96:97], v[96:97], v[196:197] op_sel_hi:[1,0]
	v_pk_mul_f32 v[98:99], v[98:99], v[196:197] op_sel_hi:[1,0]
	v_sub_f32_e32 v164, v240, v164
	v_sub_f32_e32 v165, v241, v165
	v_sub_f32_e32 v166, v242, v166
	v_sub_f32_e32 v167, v243, v167
	s_waitcnt lgkmcnt(3)
	v_mfma_f32_16x16x32_bf16 v[172:175], v[212:215], v[140:143], v[172:175]
	ds_read_b128 v[228:231], v2 offset:19456
	v_lshlrev_b32_e32 v240, 16, v194
	v_and_b32_e32 v241, 0xffff0000, v194
	v_lshlrev_b32_e32 v242, 16, v195
	v_and_b32_e32 v243, 0xffff0000, v195
	s_waitcnt lgkmcnt(3)
	v_mfma_f32_16x16x32_bf16 v[176:179], v[216:219], v[140:143], v[176:179]
	ds_read_b128 v[232:235], v2 offset:23552
	v_sub_f32_e32 v168, v240, v168
	v_sub_f32_e32 v169, v241, v169
	v_sub_f32_e32 v170, v242, v170
	v_sub_f32_e32 v171, v243, v171
	s_waitcnt lgkmcnt(3)
	v_mfma_f32_16x16x32_bf16 v[180:183], v[220:223], v[140:143], v[180:183]
	ds_read_b128 v[212:215], v2 offset:27648
	v_cvt_pk_bf16_f32 v152, v164, v165
	v_cvt_pk_bf16_f32 v153, v166, v167
	v_cvt_pk_bf16_f32 v154, v168, v169
	v_cvt_pk_bf16_f32 v155, v170, v171
	s_waitcnt lgkmcnt(3)
	v_mfma_f32_16x16x32_bf16 v[184:187], v[224:227], v[140:143], v[184:187]
	ds_read_b128 v[216:219], v2 offset:31744
	s_waitcnt lgkmcnt(3)
	v_mfma_f32_16x16x32_bf16 v[172:175], v[228:231], v[144:147], v[172:175]
	ds_read_b128 v[220:223], v2 offset:49152
	s_cmp_eq_u32 s6, 0
	s_cbranch_scc1 .Lscan_noegl
	v_lshl_add_u64 v[240:241], v[100:101], 0, s[0:1]
	global_load_dword v196, v[240:241], off offset:4
.Lscan_noegl:
	s_waitcnt lgkmcnt(3)
	v_mfma_f32_16x16x32_bf16 v[176:179], v[232:235], v[144:147], v[176:179]
	ds_read_b128 v[224:227], v2 offset:51200
	s_cmp_lt_u32 s6, 2
	s_cbranch_scc1 .Lscan_notouch
	global_load_dword v238, v[236:237], off
	global_load_dword v238, v[236:237], off offset:64
	global_load_dword v238, v[236:237], off offset:128
	global_load_dword v238, v[236:237], off offset:192
.Lscan_notouch:
	s_waitcnt lgkmcnt(3)
	v_mfma_f32_16x16x32_bf16 v[180:183], v[212:215], v[144:147], v[180:183]
	ds_read_b128 v[228:231], v2 offset:53248
	s_waitcnt lgkmcnt(3)
	v_mfma_f32_16x16x32_bf16 v[184:187], v[216:219], v[144:147], v[184:187]
	ds_read_b128 v[232:235], v2 offset:55296
	s_waitcnt lgkmcnt(3)
	v_mfma_f32_16x16x32_bf16 v[172:175], v[220:223], v[148:151], v[172:175]
	ds_read_b128 v[212:215], v2 offset:50176
	s_waitcnt lgkmcnt(3)
	v_mfma_f32_16x16x32_bf16 v[176:179], v[224:227], v[148:151], v[176:179]
	ds_read_b128 v[216:219], v2 offset:52224
	s_waitcnt lgkmcnt(3)
	v_mfma_f32_16x16x32_bf16 v[180:183], v[228:231], v[148:151], v[180:183]
	ds_read_b128 v[220:223], v2 offset:54272
	s_waitcnt lgkmcnt(3)
	v_mfma_f32_16x16x32_bf16 v[184:187], v[232:235], v[148:151], v[184:187]
	ds_read_b128 v[224:227], v2 offset:56320
	s_waitcnt lgkmcnt(3)
	v_mfma_f32_16x16x32_bf16 v[172:175], v[212:215], v[152:155], v[172:175]
	ds_read_b128 v[228:231], v2 offset:32768
	s_waitcnt lgkmcnt(3)
	v_mfma_f32_16x16x32_bf16 v[176:179], v[216:219], v[152:155], v[176:179]
	ds_read_b128 v[232:235], v2 offset:34816
	s_waitcnt lgkmcnt(3)
	v_mfma_f32_16x16x32_bf16 v[180:183], v[220:223], v[152:155], v[180:183]
	ds_read_b128 v[212:215], v2 offset:36864
	s_waitcnt lgkmcnt(3)
	v_mfma_f32_16x16x32_bf16 v[184:187], v[224:227], v[152:155], v[184:187]
	ds_read_b128 v[216:219], v2 offset:38912
	s_waitcnt lgkmcnt(3)
	v_mfma_f32_16x16x32_bf16 v[16:19], v[228:231], v[148:151], v[16:19]
	ds_read_b128 v[220:223], v2 offset:40960
	s_waitcnt lgkmcnt(3)
	v_mfma_f32_16x16x32_bf16 v[4:7], v[232:235], v[148:151], v[4:7]
	ds_read_b128 v[224:227], v2 offset:43008
	v_bfe_u32 v156, v172, 16, 1
	v_add3_u32 v156, v172, v156, s43
	global_store_short_d16_hi v197, v156, s[86:87]
	v_bfe_u32 v157, v173, 16, 1
	v_add3_u32 v157, v173, v157, s43
	v_add_u32_e32 v189, 0x1c00, v197
	global_store_short_d16_hi v189, v157, s[86:87]
	s_waitcnt lgkmcnt(3)
	v_mfma_f32_16x16x32_bf16 v[44:47], v[212:215], v[148:151], v[44:47]
	ds_read_b128 v[228:231], v2 offset:45056
	v_bfe_u32 v158, v174, 16, 1
	v_add3_u32 v158, v174, v158, s43
	v_add_u32_e32 v190, 0x3800, v197
	global_store_short_d16_hi v190, v158, s[86:87]
	v_bfe_u32 v159, v175, 16, 1
	v_add3_u32 v159, v175, v159, s43
	v_add_u32_e32 v191, 0x5400, v197
	global_store_short_d16_hi v191, v159, s[86:87]
	s_waitcnt lgkmcnt(3)
	v_mfma_f32_16x16x32_bf16 v[76:79], v[216:219], v[148:151], v[76:79]
	ds_read_b128 v[232:235], v2 offset:47104
	s_waitcnt lgkmcnt(3)
	v_mfma_f32_16x16x32_bf16 v[84:87], v[220:223], v[148:151], v[84:87]
	ds_read_b128 v[212:215], v2 offset:33792
	v_bfe_u32 v160, v176, 16, 1
	v_add3_u32 v160, v176, v160, s43
	v_add_u32_e32 v192, 0x1c000, v197
	global_store_short_d16_hi v192, v160, s[86:87]
	v_bfe_u32 v161, v177, 16, 1
	v_add3_u32 v161, v177, v161, s43
	v_add_u32_e32 v193, 0x1dc00, v197
	global_store_short_d16_hi v193, v161, s[86:87]
	s_waitcnt lgkmcnt(3)
	v_mfma_f32_16x16x32_bf16 v[88:91], v[224:227], v[148:151], v[88:91]
	ds_read_b128 v[216:219], v2 offset:35840
	v_bfe_u32 v162, v178, 16, 1
	v_add3_u32 v162, v178, v162, s43
	v_add_u32_e32 v194, 0x1f800, v197
	global_store_short_d16_hi v194, v162, s[86:87]
	v_bfe_u32 v163, v179, 16, 1
	v_add3_u32 v163, v179, v163, s43
	v_add_u32_e32 v195, 0x21400, v197
	global_store_short_d16_hi v195, v163, s[86:87]
	s_waitcnt lgkmcnt(3)
	v_mfma_f32_16x16x32_bf16 v[92:95], v[228:231], v[148:151], v[92:95]
	ds_read_b128 v[220:223], v2 offset:37888
	s_waitcnt lgkmcnt(3)
	v_mfma_f32_16x16x32_bf16 v[96:99], v[232:235], v[148:151], v[96:99]
	ds_read_b128 v[224:227], v2 offset:39936
	v_bfe_u32 v156, v180, 16, 1
	v_add3_u32 v156, v180, v156, s43
	v_add_u32_e32 v188, 0x38000, v197
	global_store_short_d16_hi v188, v156, s[86:87]
	v_bfe_u32 v157, v181, 16, 1
	v_add3_u32 v157, v181, v157, s43
	v_add_u32_e32 v189, 0x39c00, v197
	global_store_short_d16_hi v189, v157, s[86:87]
	s_waitcnt lgkmcnt(3)
	v_mfma_f32_16x16x32_bf16 v[16:19], v[212:215], v[152:155], v[16:19]
	ds_read_b128 v[228:231], v2 offset:41984
	v_bfe_u32 v158, v182, 16, 1
	v_add3_u32 v158, v182, v158, s43
	v_add_u32_e32 v190, 0x3b800, v197
	global_store_short_d16_hi v190, v158, s[86:87]
	v_bfe_u32 v159, v183, 16, 1
	v_add3_u32 v159, v183, v159, s43
	v_add_u32_e32 v191, 0x3d400, v197
	global_store_short_d16_hi v191, v159, s[86:87]
	s_waitcnt lgkmcnt(3)
	v_mfma_f32_16x16x32_bf16 v[4:7], v[216:219], v[152:155], v[4:7]
	ds_read_b128 v[232:235], v2 offset:44032
	s_waitcnt lgkmcnt(3)
	v_mfma_f32_16x16x32_bf16 v[44:47], v[220:223], v[152:155], v[44:47]
	ds_read_b128 v[212:215], v2 offset:46080
	v_bfe_u32 v160, v184, 16, 1
	v_add3_u32 v160, v184, v160, s43
	v_add_u32_e32 v192, 0x54000, v197
	global_store_short_d16_hi v192, v160, s[86:87]
	v_bfe_u32 v161, v185, 16, 1
	v_add3_u32 v161, v185, v161, s43
	v_add_u32_e32 v193, 0x55c00, v197
	global_store_short_d16_hi v193, v161, s[86:87]
	s_waitcnt lgkmcnt(3)
	v_mfma_f32_16x16x32_bf16 v[76:79], v[224:227], v[152:155], v[76:79]
	ds_read_b128 v[216:219], v2 offset:48128
	v_bfe_u32 v162, v186, 16, 1
	v_add3_u32 v162, v186, v162, s43
	v_add_u32_e32 v194, 0x57800, v197
	global_store_short_d16_hi v194, v162, s[86:87]
	v_bfe_u32 v163, v187, 16, 1
	v_add3_u32 v163, v187, v163, s43
	v_add_u32_e32 v195, 0x59400, v197
	global_store_short_d16_hi v195, v163, s[86:87]
	s_waitcnt lgkmcnt(3)
	v_mfma_f32_16x16x32_bf16 v[84:87], v[228:231], v[152:155], v[84:87]
	s_waitcnt lgkmcnt(2)
	v_mfma_f32_16x16x32_bf16 v[88:91], v[232:235], v[152:155], v[88:91]
	s_waitcnt lgkmcnt(1)
	v_mfma_f32_16x16x32_bf16 v[92:95], v[212:215], v[152:155], v[92:95]
	s_waitcnt lgkmcnt(0)
	v_mfma_f32_16x16x32_bf16 v[96:99], v[216:219], v[152:155], v[96:99]
	s_andn2_b64 vcc, exec, s[4:5]
	s_waitcnt lgkmcnt(0)
	s_barrier
	s_cbranch_vccnz .LBB0_489
	s_cmp_lt_u32 s6, 2
	s_cbranch_scc1 .Lscan_w16
	s_waitcnt vmcnt(20)
	s_branch .Lscan_wd
.Lscan_w16:
	s_waitcnt vmcnt(16)
.Lscan_wd:
	ds_write_b128 v1, v[8:11]
	ds_write_b128 v1, v[48:51] offset:32768
	ds_write_b128 v124, v[12:15]
	ds_write_b128 v124, v[52:55] offset:32768
	ds_write_b128 v125, v[20:23]
	ds_write_b128 v125, v[56:59] offset:32768
	ds_write_b128 v126, v[24:27]
	ds_write_b128 v126, v[60:63] offset:32768
	ds_write_b128 v127, v[28:31]
	ds_write_b128 v127, v[64:67] offset:32768
	ds_write_b128 v128, v[32:35]
	ds_write_b128 v128, v[68:71] offset:32768
	ds_write_b128 v129, v[36:39]
	ds_write_b128 v129, v[72:75] offset:32768
	ds_write_b128 v130, v[40:43]
	ds_write_b128 v130, v[80:83] offset:32768
	s_branch .LBB0_489
